# retention group-norm pass: 64-lane sums with in-place DPP adds and lane-swap ops instead of copies plus v_readlane/SGPR adds (same association)
# speedup vs baseline: 1.0052x; 1.0003x over previous
.LBB0_637:
	v_lshl_add_u32 v4, v161, 2, 0
	v_add_u32_e32 v0, s58, v4
	ds_read_b128 v[0:3], v0
	s_lshl_b64 s[2:3], s[20:21], 12
	s_add_u32 s6, s68, s2
	s_addc_u32 s7, s69, s3
	s_waitcnt lgkmcnt(0)
	v_mov_b32_e32 v6, v1
	v_mov_b32_e32 v7, v2
	v_mov_b32_e32 v8, v0
	v_mov_b32_e32 v9, v3
	v_pk_add_f32 v[6:7], v[6:7], v[8:9]
	s_nop 0
	v_add_f32_e32 v5, v6, v7
	s_nop 1
	v_add_f32_dpp v5, v5, v5 quad_perm:[1,0,3,2] row_mask:0xf bank_mask:0xf
	s_nop 1
	v_add_f32_dpp v5, v5, v5 quad_perm:[2,3,0,1] row_mask:0xf bank_mask:0xf
	s_nop 1
	v_add_f32_dpp v5, v5, v5 row_half_mirror row_mask:0xf bank_mask:0xf
	s_nop 1
	v_add_f32_dpp v5, v5, v5 row_mirror row_mask:0xf bank_mask:0xf
	v_mov_b32_e32 v6, v5
	s_nop 1
	v_permlane16_swap_b32_e32 v5, v6
	v_add_f32_e32 v5, v5, v6
	v_mov_b32_e32 v6, v5
	s_nop 1
	v_permlane32_swap_b32_e32 v5, v6
	v_add_f32_e32 v5, v5, v6
	v_fmamk_f32 v1, v5, 0xbb800000, v1
	v_fmamk_f32 v0, v5, 0xbb800000, v0
	v_fmamk_f32 v3, v5, 0xbb800000, v3
	v_fmac_f32_e32 v2, 0xbb800000, v5
	v_pk_mul_f32 v[6:7], v[2:3], v[2:3]
	v_pk_mul_f32 v[8:9], v[0:1], v[0:1]
	s_nop 0
	v_pk_mov_b32 v[10:11], v[8:9], v[6:7] op_sel:[1,0]
	v_mov_b32_e32 v9, v7
	v_pk_add_f32 v[6:7], v[10:11], v[8:9]
	s_nop 0
	v_add_f32_e32 v5, v6, v7
	s_nop 1
	v_add_f32_dpp v5, v5, v5 quad_perm:[1,0,3,2] row_mask:0xf bank_mask:0xf
	s_nop 1
	v_add_f32_dpp v5, v5, v5 quad_perm:[2,3,0,1] row_mask:0xf bank_mask:0xf
	s_nop 1
	v_add_f32_dpp v5, v5, v5 row_half_mirror row_mask:0xf bank_mask:0xf
	s_nop 1
	v_add_f32_dpp v5, v5, v5 row_mirror row_mask:0xf bank_mask:0xf
	v_mov_b32_e32 v6, v5
	s_nop 1
	v_permlane16_swap_b32_e32 v5, v6
	v_add_f32_e32 v5, v5, v6
	v_mov_b32_e32 v6, v5
	s_nop 1
	v_permlane32_swap_b32_e32 v5, v6
	v_add_f32_e32 v5, v5, v6
	v_fmamk_f32 v5, v5, 0x3b800000, v251
	v_cmp_gt_f32_e32 vcc, s19, v5
	v_mul_f32_e32 v6, 0x4f800000, v5
	s_nop 0
	v_cndmask_b32_e32 v5, v5, v6, vcc
	v_sqrt_f32_e32 v6, v5
	s_nop 0
	v_add_u32_e32 v7, -1, v6
	v_fma_f32 v8, -v7, v6, v5
	v_cmp_ge_f32_e64 s[2:3], 0, v8
	v_add_u32_e32 v8, 1, v6
	s_nop 0
	v_cndmask_b32_e64 v7, v6, v7, s[2:3]
	v_fma_f32 v6, -v8, v6, v5
	v_cmp_lt_f32_e64 s[2:3], 0, v6
	s_nop 1
	v_cndmask_b32_e64 v6, v7, v8, s[2:3]
	v_mul_f32_e32 v7, 0x37800000, v6
	v_cndmask_b32_e32 v6, v6, v7, vcc
	v_cmp_class_f32_e32 vcc, v5, v252
	s_nop 1
	v_cndmask_b32_e32 v5, v6, v5, vcc
	v_div_scale_f32 v6, s[2:3], v5, v5, 1.0
	v_rcp_f32_e32 v7, v6
	s_or_b32 s2, s54, s59
	v_or_b32_e32 v212, s2, v161
	v_fma_f32 v8, -v6, v7, 1.0
	v_fmac_f32_e32 v7, v8, v7
	v_div_scale_f32 v8, vcc, 1.0, v5, 1.0
	v_mul_f32_e32 v9, v8, v7
	v_fma_f32 v10, -v6, v9, v8
	v_fmac_f32_e32 v9, v10, v7
	v_fma_f32 v6, -v6, v9, v8
	v_div_fmas_f32 v6, v6, v7, v9
	v_div_fixup_f32 v6, v6, v5, 1.0
	v_pk_mul_f32 v[0:1], v[0:1], v[6:7] op_sel_hi:[1,0]
	s_waitcnt vmcnt(15)
	v_lshlrev_b32_e32 v8, 16, v158
	v_and_b32_e32 v9, 0xffff0000, v158
	v_pk_mul_f32 v[2:3], v[2:3], v[6:7] op_sel_hi:[1,0]
	v_lshlrev_b32_e32 v6, 16, v159
	v_and_b32_e32 v7, 0xffff0000, v159
	v_pk_mul_f32 v[0:1], v[0:1], v[8:9]
	v_pk_mul_f32 v[2:3], v[2:3], v[6:7]
	v_cvt_pk_bf16_f32 v0, v0, v1
	v_cvt_pk_bf16_f32 v1, v2, v3
	v_lshl_add_u64 v[2:3], v[212:213], 1, s[6:7]
	global_store_dwordx2 v[2:3], v[0:1], off
	v_add_u32_e32 v0, s60, v4
	ds_read_b128 v[0:3], v0
	s_waitcnt lgkmcnt(0)
	v_mov_b32_e32 v6, v1
	v_mov_b32_e32 v7, v2
	v_mov_b32_e32 v8, v0
	v_mov_b32_e32 v9, v3
	v_pk_add_f32 v[6:7], v[6:7], v[8:9]
	s_nop 0
	v_add_f32_e32 v5, v6, v7
	s_nop 1
	v_add_f32_dpp v5, v5, v5 quad_perm:[1,0,3,2] row_mask:0xf bank_mask:0xf
	s_nop 1
	v_add_f32_dpp v5, v5, v5 quad_perm:[2,3,0,1] row_mask:0xf bank_mask:0xf
	s_nop 1
	v_add_f32_dpp v5, v5, v5 row_half_mirror row_mask:0xf bank_mask:0xf
	s_nop 1
	v_add_f32_dpp v5, v5, v5 row_mirror row_mask:0xf bank_mask:0xf
	v_mov_b32_e32 v6, v5
	s_nop 1
	v_permlane16_swap_b32_e32 v5, v6
	v_add_f32_e32 v5, v5, v6
	v_mov_b32_e32 v6, v5
	s_nop 1
	v_permlane32_swap_b32_e32 v5, v6
	v_add_f32_e32 v5, v5, v6
	v_fmamk_f32 v1, v5, 0xbb800000, v1
	v_fmamk_f32 v0, v5, 0xbb800000, v0
	v_fmamk_f32 v3, v5, 0xbb800000, v3
	v_fmac_f32_e32 v2, 0xbb800000, v5
	v_pk_mul_f32 v[6:7], v[2:3], v[2:3]
	v_pk_mul_f32 v[8:9], v[0:1], v[0:1]
	s_nop 0
	v_pk_mov_b32 v[10:11], v[8:9], v[6:7] op_sel:[1,0]
	v_mov_b32_e32 v9, v7
	v_pk_add_f32 v[6:7], v[10:11], v[8:9]
	s_nop 0
	v_add_f32_e32 v5, v6, v7
	s_nop 1
	v_add_f32_dpp v5, v5, v5 quad_perm:[1,0,3,2] row_mask:0xf bank_mask:0xf
	s_nop 1
	v_add_f32_dpp v5, v5, v5 quad_perm:[2,3,0,1] row_mask:0xf bank_mask:0xf
	s_nop 1
	v_add_f32_dpp v5, v5, v5 row_half_mirror row_mask:0xf bank_mask:0xf
	s_nop 1
	v_add_f32_dpp v5, v5, v5 row_mirror row_mask:0xf bank_mask:0xf
	v_mov_b32_e32 v6, v5
	s_nop 1
	v_permlane16_swap_b32_e32 v5, v6
	v_add_f32_e32 v5, v5, v6
	v_mov_b32_e32 v6, v5
	s_nop 1
	v_permlane32_swap_b32_e32 v5, v6
	v_add_f32_e32 v5, v5, v6
	v_fmamk_f32 v5, v5, 0x3b800000, v251
	v_cmp_gt_f32_e32 vcc, s19, v5
	v_mul_f32_e32 v6, 0x4f800000, v5
	s_nop 0
	v_cndmask_b32_e32 v5, v5, v6, vcc
	v_sqrt_f32_e32 v6, v5
	s_nop 0
	v_add_u32_e32 v7, -1, v6
	v_fma_f32 v8, -v7, v6, v5
	v_cmp_ge_f32_e64 s[2:3], 0, v8
	v_add_u32_e32 v8, 1, v6
	s_nop 0
	v_cndmask_b32_e64 v7, v6, v7, s[2:3]
	v_fma_f32 v6, -v8, v6, v5
	v_cmp_lt_f32_e64 s[2:3], 0, v6
	s_nop 1
	v_cndmask_b32_e64 v6, v7, v8, s[2:3]
	v_mul_f32_e32 v7, 0x37800000, v6
	v_cndmask_b32_e32 v6, v6, v7, vcc
	v_cmp_class_f32_e32 vcc, v5, v252
	s_nop 1
	v_cndmask_b32_e32 v5, v6, v5, vcc
	v_div_scale_f32 v6, s[2:3], v5, v5, 1.0
	v_rcp_f32_e32 v7, v6
	s_or_b32 s2, s54, s61
	v_or_b32_e32 v212, s2, v161
	v_fma_f32 v8, -v6, v7, 1.0
	v_fmac_f32_e32 v7, v8, v7
	v_div_scale_f32 v8, vcc, 1.0, v5, 1.0
	v_mul_f32_e32 v9, v8, v7
	v_fma_f32 v10, -v6, v9, v8
	v_fmac_f32_e32 v9, v10, v7
	v_fma_f32 v6, -v6, v9, v8
	v_div_fmas_f32 v6, v6, v7, v9
	v_div_fixup_f32 v6, v6, v5, 1.0
	v_pk_mul_f32 v[0:1], v[0:1], v[6:7] op_sel_hi:[1,0]
	s_waitcnt vmcnt(15)
	v_lshlrev_b32_e32 v8, 16, v156
	v_and_b32_e32 v9, 0xffff0000, v156
	v_pk_mul_f32 v[2:3], v[2:3], v[6:7] op_sel_hi:[1,0]
	v_lshlrev_b32_e32 v6, 16, v157
	v_and_b32_e32 v7, 0xffff0000, v157
	v_pk_mul_f32 v[0:1], v[0:1], v[8:9]
	v_pk_mul_f32 v[2:3], v[2:3], v[6:7]
	v_cvt_pk_bf16_f32 v0, v0, v1
	v_cvt_pk_bf16_f32 v1, v2, v3
	v_lshl_add_u64 v[2:3], v[212:213], 1, s[6:7]
	global_store_dwordx2 v[2:3], v[0:1], off
	v_add_u32_e32 v0, s62, v4
	ds_read_b128 v[0:3], v0
	s_waitcnt lgkmcnt(0)
	v_mov_b32_e32 v6, v1
	v_mov_b32_e32 v7, v2
	v_mov_b32_e32 v8, v0
	v_mov_b32_e32 v9, v3
	v_pk_add_f32 v[6:7], v[6:7], v[8:9]
	s_nop 0
	v_add_f32_e32 v5, v6, v7
	s_nop 1
	v_add_f32_dpp v5, v5, v5 quad_perm:[1,0,3,2] row_mask:0xf bank_mask:0xf
	s_nop 1
	v_add_f32_dpp v5, v5, v5 quad_perm:[2,3,0,1] row_mask:0xf bank_mask:0xf
	s_nop 1
	v_add_f32_dpp v5, v5, v5 row_half_mirror row_mask:0xf bank_mask:0xf
	s_nop 1
	v_add_f32_dpp v5, v5, v5 row_mirror row_mask:0xf bank_mask:0xf
	v_mov_b32_e32 v6, v5
	s_nop 1
	v_permlane16_swap_b32_e32 v5, v6
	v_add_f32_e32 v5, v5, v6
	v_mov_b32_e32 v6, v5
	s_nop 1
	v_permlane32_swap_b32_e32 v5, v6
	v_add_f32_e32 v5, v5, v6
	v_fmamk_f32 v1, v5, 0xbb800000, v1
	v_fmamk_f32 v0, v5, 0xbb800000, v0
	v_fmamk_f32 v3, v5, 0xbb800000, v3
	v_fmac_f32_e32 v2, 0xbb800000, v5
	v_pk_mul_f32 v[6:7], v[2:3], v[2:3]
	v_pk_mul_f32 v[8:9], v[0:1], v[0:1]
	s_nop 0
	v_pk_mov_b32 v[10:11], v[8:9], v[6:7] op_sel:[1,0]
	v_mov_b32_e32 v9, v7
	v_pk_add_f32 v[6:7], v[10:11], v[8:9]
	s_nop 0
	v_add_f32_e32 v5, v6, v7
	s_nop 1
	v_add_f32_dpp v5, v5, v5 quad_perm:[1,0,3,2] row_mask:0xf bank_mask:0xf
	s_nop 1
	v_add_f32_dpp v5, v5, v5 quad_perm:[2,3,0,1] row_mask:0xf bank_mask:0xf
	s_nop 1
	v_add_f32_dpp v5, v5, v5 row_half_mirror row_mask:0xf bank_mask:0xf
	s_nop 1
	v_add_f32_dpp v5, v5, v5 row_mirror row_mask:0xf bank_mask:0xf
	v_mov_b32_e32 v6, v5
	s_nop 1
	v_permlane16_swap_b32_e32 v5, v6
	v_add_f32_e32 v5, v5, v6
	v_mov_b32_e32 v6, v5
	s_nop 1
	v_permlane32_swap_b32_e32 v5, v6
	v_add_f32_e32 v5, v5, v6
	v_fmamk_f32 v5, v5, 0x3b800000, v251
	v_cmp_gt_f32_e32 vcc, s19, v5
	v_mul_f32_e32 v6, 0x4f800000, v5
	s_nop 0
	v_cndmask_b32_e32 v5, v5, v6, vcc
	v_sqrt_f32_e32 v6, v5
	s_nop 0
	v_add_u32_e32 v7, -1, v6
	v_fma_f32 v8, -v7, v6, v5
	v_cmp_ge_f32_e64 s[2:3], 0, v8
	v_add_u32_e32 v8, 1, v6
	s_nop 0
	v_cndmask_b32_e64 v7, v6, v7, s[2:3]
	v_fma_f32 v6, -v8, v6, v5
	v_cmp_lt_f32_e64 s[2:3], 0, v6
	s_nop 1
	v_cndmask_b32_e64 v6, v7, v8, s[2:3]
	v_mul_f32_e32 v7, 0x37800000, v6
	v_cndmask_b32_e32 v6, v6, v7, vcc
	v_cmp_class_f32_e32 vcc, v5, v252
	s_nop 1
	v_cndmask_b32_e32 v5, v6, v5, vcc
	v_div_scale_f32 v6, s[2:3], v5, v5, 1.0
	v_rcp_f32_e32 v7, v6
	s_or_b32 s2, s54, s63
	v_or_b32_e32 v212, s2, v161
	v_fma_f32 v8, -v6, v7, 1.0
	v_fmac_f32_e32 v7, v8, v7
	v_div_scale_f32 v8, vcc, 1.0, v5, 1.0
	v_mul_f32_e32 v9, v8, v7
	v_fma_f32 v10, -v6, v9, v8
	v_fmac_f32_e32 v9, v10, v7
	v_fma_f32 v6, -v6, v9, v8
	v_div_fmas_f32 v6, v6, v7, v9
	v_div_fixup_f32 v6, v6, v5, 1.0
	v_pk_mul_f32 v[0:1], v[0:1], v[6:7] op_sel_hi:[1,0]
	s_waitcnt vmcnt(15)
	v_lshlrev_b32_e32 v8, 16, v154
	v_and_b32_e32 v9, 0xffff0000, v154
	v_pk_mul_f32 v[2:3], v[2:3], v[6:7] op_sel_hi:[1,0]
	v_lshlrev_b32_e32 v6, 16, v155
	v_and_b32_e32 v7, 0xffff0000, v155
	v_pk_mul_f32 v[0:1], v[0:1], v[8:9]
	v_pk_mul_f32 v[2:3], v[2:3], v[6:7]
	v_cvt_pk_bf16_f32 v0, v0, v1
	v_cvt_pk_bf16_f32 v1, v2, v3
	v_lshl_add_u64 v[2:3], v[212:213], 1, s[6:7]
	global_store_dwordx2 v[2:3], v[0:1], off
	v_add_u32_e32 v0, s64, v4
	ds_read_b128 v[0:3], v0
	s_waitcnt lgkmcnt(0)
	v_mov_b32_e32 v6, v1
	v_mov_b32_e32 v7, v2
	v_mov_b32_e32 v8, v0
	v_mov_b32_e32 v9, v3
	v_pk_add_f32 v[6:7], v[6:7], v[8:9]
	s_nop 0
	v_add_f32_e32 v5, v6, v7
	s_nop 1
	v_add_f32_dpp v5, v5, v5 quad_perm:[1,0,3,2] row_mask:0xf bank_mask:0xf
	s_nop 1
	v_add_f32_dpp v5, v5, v5 quad_perm:[2,3,0,1] row_mask:0xf bank_mask:0xf
	s_nop 1
	v_add_f32_dpp v5, v5, v5 row_half_mirror row_mask:0xf bank_mask:0xf
	s_nop 1
	v_add_f32_dpp v5, v5, v5 row_mirror row_mask:0xf bank_mask:0xf
	v_mov_b32_e32 v6, v5
	s_nop 1
	v_permlane16_swap_b32_e32 v5, v6
	v_add_f32_e32 v5, v5, v6
	v_mov_b32_e32 v6, v5
	s_nop 1
	v_permlane32_swap_b32_e32 v5, v6
	v_add_f32_e32 v5, v5, v6
	v_fmamk_f32 v1, v5, 0xbb800000, v1
	v_fmamk_f32 v0, v5, 0xbb800000, v0
	v_fmamk_f32 v3, v5, 0xbb800000, v3
	v_fmac_f32_e32 v2, 0xbb800000, v5
	v_pk_mul_f32 v[6:7], v[2:3], v[2:3]
	v_pk_mul_f32 v[8:9], v[0:1], v[0:1]
	s_nop 0
	v_pk_mov_b32 v[10:11], v[8:9], v[6:7] op_sel:[1,0]
	v_mov_b32_e32 v9, v7
	v_pk_add_f32 v[6:7], v[10:11], v[8:9]
	s_nop 0
	v_add_f32_e32 v5, v6, v7
	s_nop 1
	v_add_f32_dpp v5, v5, v5 quad_perm:[1,0,3,2] row_mask:0xf bank_mask:0xf
	s_nop 1
	v_add_f32_dpp v5, v5, v5 quad_perm:[2,3,0,1] row_mask:0xf bank_mask:0xf
	s_nop 1
	v_add_f32_dpp v5, v5, v5 row_half_mirror row_mask:0xf bank_mask:0xf
	s_nop 1
	v_add_f32_dpp v5, v5, v5 row_mirror row_mask:0xf bank_mask:0xf
	v_mov_b32_e32 v6, v5
	s_nop 1
	v_permlane16_swap_b32_e32 v5, v6
	v_add_f32_e32 v5, v5, v6
	v_mov_b32_e32 v6, v5
	s_nop 1
	v_permlane32_swap_b32_e32 v5, v6
	v_add_f32_e32 v5, v5, v6
	v_fmamk_f32 v5, v5, 0x3b800000, v251
	v_cmp_gt_f32_e32 vcc, s19, v5
	v_mul_f32_e32 v6, 0x4f800000, v5
	s_nop 0
	v_cndmask_b32_e32 v5, v5, v6, vcc
	v_sqrt_f32_e32 v6, v5
	s_nop 0
	v_add_u32_e32 v7, -1, v6
	v_fma_f32 v8, -v7, v6, v5
	v_cmp_ge_f32_e64 s[2:3], 0, v8
	v_add_u32_e32 v8, 1, v6
	s_nop 0
	v_cndmask_b32_e64 v7, v6, v7, s[2:3]
	v_fma_f32 v6, -v8, v6, v5
	v_cmp_lt_f32_e64 s[2:3], 0, v6
	s_nop 1
	v_cndmask_b32_e64 v6, v7, v8, s[2:3]
	v_mul_f32_e32 v7, 0x37800000, v6
	v_cndmask_b32_e32 v6, v6, v7, vcc
	v_cmp_class_f32_e32 vcc, v5, v252
	s_nop 1
	v_cndmask_b32_e32 v5, v6, v5, vcc
	v_div_scale_f32 v6, s[2:3], v5, v5, 1.0
	v_rcp_f32_e32 v7, v6
	s_or_b32 s2, s54, s65
	v_or_b32_e32 v212, s2, v161
	v_fma_f32 v8, -v6, v7, 1.0
	v_fmac_f32_e32 v7, v8, v7
	v_div_scale_f32 v8, vcc, 1.0, v5, 1.0
	v_mul_f32_e32 v9, v8, v7
	v_fma_f32 v10, -v6, v9, v8
	v_fmac_f32_e32 v9, v10, v7
	v_fma_f32 v6, -v6, v9, v8
	v_div_fmas_f32 v6, v6, v7, v9
	v_div_fixup_f32 v6, v6, v5, 1.0
	v_pk_mul_f32 v[0:1], v[0:1], v[6:7] op_sel_hi:[1,0]
	s_waitcnt vmcnt(15)
	v_lshlrev_b32_e32 v8, 16, v152
	v_and_b32_e32 v9, 0xffff0000, v152
	v_pk_mul_f32 v[2:3], v[2:3], v[6:7] op_sel_hi:[1,0]
	v_lshlrev_b32_e32 v6, 16, v153
	v_and_b32_e32 v7, 0xffff0000, v153
	v_pk_mul_f32 v[0:1], v[0:1], v[8:9]
	v_pk_mul_f32 v[2:3], v[2:3], v[6:7]
	v_cvt_pk_bf16_f32 v0, v0, v1
	v_cvt_pk_bf16_f32 v1, v2, v3
	v_lshl_add_u64 v[2:3], v[212:213], 1, s[6:7]
	global_store_dwordx2 v[2:3], v[0:1], off
	v_add_u32_e32 v0, s78, v4
	ds_read_b128 v[0:3], v0
	s_waitcnt lgkmcnt(0)
	v_mov_b32_e32 v6, v1
	v_mov_b32_e32 v7, v2
	v_mov_b32_e32 v8, v0
	v_mov_b32_e32 v9, v3
	v_pk_add_f32 v[6:7], v[6:7], v[8:9]
	s_nop 0
	v_add_f32_e32 v5, v6, v7
	s_nop 1
	v_add_f32_dpp v5, v5, v5 quad_perm:[1,0,3,2] row_mask:0xf bank_mask:0xf
	s_nop 1
	v_add_f32_dpp v5, v5, v5 quad_perm:[2,3,0,1] row_mask:0xf bank_mask:0xf
	s_nop 1
	v_add_f32_dpp v5, v5, v5 row_half_mirror row_mask:0xf bank_mask:0xf
	s_nop 1
	v_add_f32_dpp v5, v5, v5 row_mirror row_mask:0xf bank_mask:0xf
	v_mov_b32_e32 v6, v5
	s_nop 1
	v_permlane16_swap_b32_e32 v5, v6
	v_add_f32_e32 v5, v5, v6
	v_mov_b32_e32 v6, v5
	s_nop 1
	v_permlane32_swap_b32_e32 v5, v6
	v_add_f32_e32 v5, v5, v6
	v_fmamk_f32 v1, v5, 0xbb800000, v1
	v_fmamk_f32 v0, v5, 0xbb800000, v0
	v_fmamk_f32 v3, v5, 0xbb800000, v3
	v_fmac_f32_e32 v2, 0xbb800000, v5
	v_pk_mul_f32 v[6:7], v[2:3], v[2:3]
	v_pk_mul_f32 v[8:9], v[0:1], v[0:1]
	s_nop 0
	v_pk_mov_b32 v[10:11], v[8:9], v[6:7] op_sel:[1,0]
	v_mov_b32_e32 v9, v7
	v_pk_add_f32 v[6:7], v[10:11], v[8:9]
	s_nop 0
	v_add_f32_e32 v5, v6, v7
	s_nop 1
	v_add_f32_dpp v5, v5, v5 quad_perm:[1,0,3,2] row_mask:0xf bank_mask:0xf
	s_nop 1
	v_add_f32_dpp v5, v5, v5 quad_perm:[2,3,0,1] row_mask:0xf bank_mask:0xf
	s_nop 1
	v_add_f32_dpp v5, v5, v5 row_half_mirror row_mask:0xf bank_mask:0xf
	s_nop 1
	v_add_f32_dpp v5, v5, v5 row_mirror row_mask:0xf bank_mask:0xf
	v_mov_b32_e32 v6, v5
	s_nop 1
	v_permlane16_swap_b32_e32 v5, v6
	v_add_f32_e32 v5, v5, v6
	v_mov_b32_e32 v6, v5
	s_nop 1
	v_permlane32_swap_b32_e32 v5, v6
	v_add_f32_e32 v5, v5, v6
	v_fmamk_f32 v5, v5, 0x3b800000, v251
	v_cmp_gt_f32_e32 vcc, s19, v5
	v_mul_f32_e32 v6, 0x4f800000, v5
	s_nop 0
	v_cndmask_b32_e32 v5, v5, v6, vcc
	v_sqrt_f32_e32 v6, v5
	s_nop 0
	v_add_u32_e32 v7, -1, v6
	v_fma_f32 v8, -v7, v6, v5
	v_cmp_ge_f32_e64 s[2:3], 0, v8
	v_add_u32_e32 v8, 1, v6
	s_nop 0
	v_cndmask_b32_e64 v7, v6, v7, s[2:3]
	v_fma_f32 v6, -v8, v6, v5
	v_cmp_lt_f32_e64 s[2:3], 0, v6
	s_nop 1
	v_cndmask_b32_e64 v6, v7, v8, s[2:3]
	v_mul_f32_e32 v7, 0x37800000, v6
	v_cndmask_b32_e32 v6, v6, v7, vcc
	v_cmp_class_f32_e32 vcc, v5, v252
	s_nop 1
	v_cndmask_b32_e32 v5, v6, v5, vcc
	v_div_scale_f32 v6, s[2:3], v5, v5, 1.0
	v_rcp_f32_e32 v7, v6
	s_or_b32 s2, s54, s79
	v_or_b32_e32 v212, s2, v161
	v_fma_f32 v8, -v6, v7, 1.0
	v_fmac_f32_e32 v7, v8, v7
	v_div_scale_f32 v8, vcc, 1.0, v5, 1.0
	v_mul_f32_e32 v9, v8, v7
	v_fma_f32 v10, -v6, v9, v8
	v_fmac_f32_e32 v9, v10, v7
	v_fma_f32 v6, -v6, v9, v8
	v_div_fmas_f32 v6, v6, v7, v9
	v_div_fixup_f32 v6, v6, v5, 1.0
	v_pk_mul_f32 v[0:1], v[0:1], v[6:7] op_sel_hi:[1,0]
	s_waitcnt vmcnt(15)
	v_lshlrev_b32_e32 v8, 16, v150
	v_and_b32_e32 v9, 0xffff0000, v150
	v_pk_mul_f32 v[2:3], v[2:3], v[6:7] op_sel_hi:[1,0]
	v_lshlrev_b32_e32 v6, 16, v151
	v_and_b32_e32 v7, 0xffff0000, v151
	v_pk_mul_f32 v[0:1], v[0:1], v[8:9]
	v_pk_mul_f32 v[2:3], v[2:3], v[6:7]
	v_cvt_pk_bf16_f32 v0, v0, v1
	v_cvt_pk_bf16_f32 v1, v2, v3
	v_lshl_add_u64 v[2:3], v[212:213], 1, s[6:7]
	global_store_dwordx2 v[2:3], v[0:1], off
	v_add_u32_e32 v0, s88, v4
	ds_read_b128 v[0:3], v0
	s_waitcnt lgkmcnt(0)
	v_mov_b32_e32 v6, v1
	v_mov_b32_e32 v7, v2
	v_mov_b32_e32 v8, v0
	v_mov_b32_e32 v9, v3
	v_pk_add_f32 v[6:7], v[6:7], v[8:9]
	s_nop 0
	v_add_f32_e32 v5, v6, v7
	s_nop 1
	v_add_f32_dpp v5, v5, v5 quad_perm:[1,0,3,2] row_mask:0xf bank_mask:0xf
	s_nop 1
	v_add_f32_dpp v5, v5, v5 quad_perm:[2,3,0,1] row_mask:0xf bank_mask:0xf
	s_nop 1
	v_add_f32_dpp v5, v5, v5 row_half_mirror row_mask:0xf bank_mask:0xf
	s_nop 1
	v_add_f32_dpp v5, v5, v5 row_mirror row_mask:0xf bank_mask:0xf
	v_mov_b32_e32 v6, v5
	s_nop 1
	v_permlane16_swap_b32_e32 v5, v6
	v_add_f32_e32 v5, v5, v6
	v_mov_b32_e32 v6, v5
	s_nop 1
	v_permlane32_swap_b32_e32 v5, v6
	v_add_f32_e32 v5, v5, v6
	v_fmamk_f32 v1, v5, 0xbb800000, v1
	v_fmamk_f32 v0, v5, 0xbb800000, v0
	v_fmamk_f32 v3, v5, 0xbb800000, v3
	v_fmac_f32_e32 v2, 0xbb800000, v5
	v_pk_mul_f32 v[6:7], v[2:3], v[2:3]
	v_pk_mul_f32 v[8:9], v[0:1], v[0:1]
	s_nop 0
	v_pk_mov_b32 v[10:11], v[8:9], v[6:7] op_sel:[1,0]
	v_mov_b32_e32 v9, v7
	v_pk_add_f32 v[6:7], v[10:11], v[8:9]
	s_nop 0
	v_add_f32_e32 v5, v6, v7
	s_nop 1
	v_add_f32_dpp v5, v5, v5 quad_perm:[1,0,3,2] row_mask:0xf bank_mask:0xf
	s_nop 1
	v_add_f32_dpp v5, v5, v5 quad_perm:[2,3,0,1] row_mask:0xf bank_mask:0xf
	s_nop 1
	v_add_f32_dpp v5, v5, v5 row_half_mirror row_mask:0xf bank_mask:0xf
	s_nop 1
	v_add_f32_dpp v5, v5, v5 row_mirror row_mask:0xf bank_mask:0xf
	v_mov_b32_e32 v6, v5
	s_nop 1
	v_permlane16_swap_b32_e32 v5, v6
	v_add_f32_e32 v5, v5, v6
	v_mov_b32_e32 v6, v5
	s_nop 1
	v_permlane32_swap_b32_e32 v5, v6
	v_add_f32_e32 v5, v5, v6
	v_fmamk_f32 v5, v5, 0x3b800000, v251
	v_cmp_gt_f32_e32 vcc, s19, v5
	v_mul_f32_e32 v6, 0x4f800000, v5
	s_nop 0
	v_cndmask_b32_e32 v5, v5, v6, vcc
	v_sqrt_f32_e32 v6, v5
	s_nop 0
	v_add_u32_e32 v7, -1, v6
	v_fma_f32 v8, -v7, v6, v5
	v_cmp_ge_f32_e64 s[2:3], 0, v8
	v_add_u32_e32 v8, 1, v6
	s_nop 0
	v_cndmask_b32_e64 v7, v6, v7, s[2:3]
	v_fma_f32 v6, -v8, v6, v5
	v_cmp_lt_f32_e64 s[2:3], 0, v6
	s_nop 1
	v_cndmask_b32_e64 v6, v7, v8, s[2:3]
	v_mul_f32_e32 v7, 0x37800000, v6
	v_cndmask_b32_e32 v6, v6, v7, vcc
	v_cmp_class_f32_e32 vcc, v5, v252
	s_nop 1
	v_cndmask_b32_e32 v5, v6, v5, vcc
	v_div_scale_f32 v6, s[2:3], v5, v5, 1.0
	v_rcp_f32_e32 v7, v6
	s_or_b32 s2, s54, s89
	v_or_b32_e32 v212, s2, v161
	v_fma_f32 v8, -v6, v7, 1.0
	v_fmac_f32_e32 v7, v8, v7
	v_div_scale_f32 v8, vcc, 1.0, v5, 1.0
	v_mul_f32_e32 v9, v8, v7
	v_fma_f32 v10, -v6, v9, v8
	v_fmac_f32_e32 v9, v10, v7
	v_fma_f32 v6, -v6, v9, v8
	v_div_fmas_f32 v6, v6, v7, v9
	v_div_fixup_f32 v6, v6, v5, 1.0
	v_pk_mul_f32 v[0:1], v[0:1], v[6:7] op_sel_hi:[1,0]
	s_waitcnt vmcnt(15)
	v_lshlrev_b32_e32 v8, 16, v148
	v_and_b32_e32 v9, 0xffff0000, v148
	v_pk_mul_f32 v[2:3], v[2:3], v[6:7] op_sel_hi:[1,0]
	v_lshlrev_b32_e32 v6, 16, v149
	v_and_b32_e32 v7, 0xffff0000, v149
	v_pk_mul_f32 v[0:1], v[0:1], v[8:9]
	v_pk_mul_f32 v[2:3], v[2:3], v[6:7]
	v_cvt_pk_bf16_f32 v0, v0, v1
	v_cvt_pk_bf16_f32 v1, v2, v3
	v_lshl_add_u64 v[2:3], v[212:213], 1, s[6:7]
	global_store_dwordx2 v[2:3], v[0:1], off
	v_add_u32_e32 v0, s94, v4
	ds_read_b128 v[0:3], v0
	s_waitcnt lgkmcnt(0)
	v_mov_b32_e32 v6, v1
	v_mov_b32_e32 v7, v2
	v_mov_b32_e32 v8, v0
	v_mov_b32_e32 v9, v3
	v_pk_add_f32 v[6:7], v[6:7], v[8:9]
	s_nop 0
	v_add_f32_e32 v5, v6, v7
	s_nop 1
	v_add_f32_dpp v5, v5, v5 quad_perm:[1,0,3,2] row_mask:0xf bank_mask:0xf
	s_nop 1
	v_add_f32_dpp v5, v5, v5 quad_perm:[2,3,0,1] row_mask:0xf bank_mask:0xf
	s_nop 1
	v_add_f32_dpp v5, v5, v5 row_half_mirror row_mask:0xf bank_mask:0xf
	s_nop 1
	v_add_f32_dpp v5, v5, v5 row_mirror row_mask:0xf bank_mask:0xf
	v_mov_b32_e32 v6, v5
	s_nop 1
	v_permlane16_swap_b32_e32 v5, v6
	v_add_f32_e32 v5, v5, v6
	v_mov_b32_e32 v6, v5
	s_nop 1
	v_permlane32_swap_b32_e32 v5, v6
	v_add_f32_e32 v5, v5, v6
	v_fmamk_f32 v1, v5, 0xbb800000, v1
	v_fmamk_f32 v0, v5, 0xbb800000, v0
	v_fmamk_f32 v3, v5, 0xbb800000, v3
	v_fmac_f32_e32 v2, 0xbb800000, v5
	v_pk_mul_f32 v[6:7], v[2:3], v[2:3]
	v_pk_mul_f32 v[8:9], v[0:1], v[0:1]
	s_nop 0
	v_pk_mov_b32 v[10:11], v[8:9], v[6:7] op_sel:[1,0]
	v_mov_b32_e32 v9, v7
	v_pk_add_f32 v[6:7], v[10:11], v[8:9]
	s_nop 0
	v_add_f32_e32 v5, v6, v7
	s_nop 1
	v_add_f32_dpp v5, v5, v5 quad_perm:[1,0,3,2] row_mask:0xf bank_mask:0xf
	s_nop 1
	v_add_f32_dpp v5, v5, v5 quad_perm:[2,3,0,1] row_mask:0xf bank_mask:0xf
	s_nop 1
	v_add_f32_dpp v5, v5, v5 row_half_mirror row_mask:0xf bank_mask:0xf
	s_nop 1
	v_add_f32_dpp v5, v5, v5 row_mirror row_mask:0xf bank_mask:0xf
	v_mov_b32_e32 v6, v5
	s_nop 1
	v_permlane16_swap_b32_e32 v5, v6
	v_add_f32_e32 v5, v5, v6
	v_mov_b32_e32 v6, v5
	s_nop 1
	v_permlane32_swap_b32_e32 v5, v6
	v_add_f32_e32 v5, v5, v6
	v_fmamk_f32 v5, v5, 0x3b800000, v251
	v_cmp_gt_f32_e32 vcc, s19, v5
	v_mul_f32_e32 v6, 0x4f800000, v5
	s_nop 0
	v_cndmask_b32_e32 v5, v5, v6, vcc
	v_sqrt_f32_e32 v6, v5
	s_nop 0
	v_add_u32_e32 v7, -1, v6
	v_fma_f32 v8, -v7, v6, v5
	v_cmp_ge_f32_e64 s[2:3], 0, v8
	v_add_u32_e32 v8, 1, v6
	s_nop 0
	v_cndmask_b32_e64 v7, v6, v7, s[2:3]
	v_fma_f32 v6, -v8, v6, v5
	v_cmp_lt_f32_e64 s[2:3], 0, v6
	s_nop 1
	v_cndmask_b32_e64 v6, v7, v8, s[2:3]
	v_mul_f32_e32 v7, 0x37800000, v6
	v_cndmask_b32_e32 v6, v6, v7, vcc
	v_cmp_class_f32_e32 vcc, v5, v252
	s_nop 1
	v_cndmask_b32_e32 v5, v6, v5, vcc
	v_div_scale_f32 v6, s[2:3], v5, v5, 1.0
	v_rcp_f32_e32 v7, v6
	s_or_b32 s2, s54, s95
	v_or_b32_e32 v212, s2, v161
	v_fma_f32 v8, -v6, v7, 1.0
	v_fmac_f32_e32 v7, v8, v7
	v_div_scale_f32 v8, vcc, 1.0, v5, 1.0
	v_mul_f32_e32 v9, v8, v7
	v_fma_f32 v10, -v6, v9, v8
	v_fmac_f32_e32 v9, v10, v7
	v_fma_f32 v6, -v6, v9, v8
	v_div_fmas_f32 v6, v6, v7, v9
	v_div_fixup_f32 v6, v6, v5, 1.0
	v_pk_mul_f32 v[0:1], v[0:1], v[6:7] op_sel_hi:[1,0]
	s_waitcnt vmcnt(15)
	v_lshlrev_b32_e32 v8, 16, v146
	v_and_b32_e32 v9, 0xffff0000, v146
	v_pk_mul_f32 v[2:3], v[2:3], v[6:7] op_sel_hi:[1,0]
	v_lshlrev_b32_e32 v6, 16, v147
	v_and_b32_e32 v7, 0xffff0000, v147
	v_pk_mul_f32 v[0:1], v[0:1], v[8:9]
	v_pk_mul_f32 v[2:3], v[2:3], v[6:7]
	v_cvt_pk_bf16_f32 v0, v0, v1
	v_cvt_pk_bf16_f32 v1, v2, v3
	v_lshl_add_u64 v[2:3], v[212:213], 1, s[6:7]
	global_store_dwordx2 v[2:3], v[0:1], off
	v_add_u32_e32 v0, s96, v4
	ds_read_b128 v[0:3], v0
	s_waitcnt lgkmcnt(0)
	v_mov_b32_e32 v6, v1
	v_mov_b32_e32 v7, v2
	v_mov_b32_e32 v8, v0
	v_mov_b32_e32 v9, v3
	v_pk_add_f32 v[6:7], v[6:7], v[8:9]
	s_nop 0
	v_add_f32_e32 v5, v6, v7
	s_nop 1
	v_add_f32_dpp v5, v5, v5 quad_perm:[1,0,3,2] row_mask:0xf bank_mask:0xf
	s_nop 1
	v_add_f32_dpp v5, v5, v5 quad_perm:[2,3,0,1] row_mask:0xf bank_mask:0xf
	s_nop 1
	v_add_f32_dpp v5, v5, v5 row_half_mirror row_mask:0xf bank_mask:0xf
	s_nop 1
	v_add_f32_dpp v5, v5, v5 row_mirror row_mask:0xf bank_mask:0xf
	v_mov_b32_e32 v6, v5
	s_nop 1
	v_permlane16_swap_b32_e32 v5, v6
	v_add_f32_e32 v5, v5, v6
	v_mov_b32_e32 v6, v5
	s_nop 1
	v_permlane32_swap_b32_e32 v5, v6
	v_add_f32_e32 v5, v5, v6
	v_fmamk_f32 v1, v5, 0xbb800000, v1
	v_fmamk_f32 v0, v5, 0xbb800000, v0
	v_fmamk_f32 v3, v5, 0xbb800000, v3
	v_fmac_f32_e32 v2, 0xbb800000, v5
	v_pk_mul_f32 v[6:7], v[2:3], v[2:3]
	v_pk_mul_f32 v[8:9], v[0:1], v[0:1]
	s_nop 0
	v_pk_mov_b32 v[10:11], v[8:9], v[6:7] op_sel:[1,0]
	v_mov_b32_e32 v9, v7
	v_pk_add_f32 v[6:7], v[10:11], v[8:9]
	s_nop 0
	v_add_f32_e32 v5, v6, v7
	s_nop 1
	v_add_f32_dpp v5, v5, v5 quad_perm:[1,0,3,2] row_mask:0xf bank_mask:0xf
	s_nop 1
	v_add_f32_dpp v5, v5, v5 quad_perm:[2,3,0,1] row_mask:0xf bank_mask:0xf
	s_nop 1
	v_add_f32_dpp v5, v5, v5 row_half_mirror row_mask:0xf bank_mask:0xf
	s_nop 1
	v_add_f32_dpp v5, v5, v5 row_mirror row_mask:0xf bank_mask:0xf
	v_mov_b32_e32 v6, v5
	s_nop 1
	v_permlane16_swap_b32_e32 v5, v6
	v_add_f32_e32 v5, v5, v6
	v_mov_b32_e32 v6, v5
	s_nop 1
	v_permlane32_swap_b32_e32 v5, v6
	v_add_f32_e32 v5, v5, v6
	v_fmamk_f32 v5, v5, 0x3b800000, v251
	v_cmp_gt_f32_e32 vcc, s19, v5
	v_mul_f32_e32 v6, 0x4f800000, v5
	s_nop 0
	v_cndmask_b32_e32 v5, v5, v6, vcc
	v_sqrt_f32_e32 v6, v5
	s_nop 0
	v_add_u32_e32 v7, -1, v6
	v_fma_f32 v8, -v7, v6, v5
	v_cmp_ge_f32_e64 s[2:3], 0, v8
	v_add_u32_e32 v8, 1, v6
	s_nop 0
	v_cndmask_b32_e64 v7, v6, v7, s[2:3]
	v_fma_f32 v6, -v8, v6, v5
	v_cmp_lt_f32_e64 s[2:3], 0, v6
	s_nop 1
	v_cndmask_b32_e64 v6, v7, v8, s[2:3]
	v_mul_f32_e32 v7, 0x37800000, v6
	v_cndmask_b32_e32 v6, v6, v7, vcc
	v_cmp_class_f32_e32 vcc, v5, v252
	s_nop 1
	v_cndmask_b32_e32 v5, v6, v5, vcc
	v_div_scale_f32 v6, s[2:3], v5, v5, 1.0
	v_rcp_f32_e32 v7, v6
	s_or_b32 s2, s54, s97
	v_or_b32_e32 v212, s2, v161
	v_fma_f32 v8, -v6, v7, 1.0
	v_fmac_f32_e32 v7, v8, v7
	v_div_scale_f32 v8, vcc, 1.0, v5, 1.0
	v_mul_f32_e32 v9, v8, v7
	v_fma_f32 v10, -v6, v9, v8
	v_fmac_f32_e32 v9, v10, v7
	v_fma_f32 v6, -v6, v9, v8
	v_div_fmas_f32 v6, v6, v7, v9
	v_div_fixup_f32 v6, v6, v5, 1.0
	v_pk_mul_f32 v[0:1], v[0:1], v[6:7] op_sel_hi:[1,0]
	s_waitcnt vmcnt(15)
	v_lshlrev_b32_e32 v8, 16, v144
	v_and_b32_e32 v9, 0xffff0000, v144
	v_pk_mul_f32 v[2:3], v[2:3], v[6:7] op_sel_hi:[1,0]
	v_lshlrev_b32_e32 v6, 16, v145
	v_and_b32_e32 v7, 0xffff0000, v145
	v_pk_mul_f32 v[0:1], v[0:1], v[8:9]
	v_pk_mul_f32 v[2:3], v[2:3], v[6:7]
	v_cvt_pk_bf16_f32 v0, v0, v1
	v_cvt_pk_bf16_f32 v1, v2, v3
	v_lshl_add_u64 v[2:3], v[212:213], 1, s[6:7]
	global_store_dwordx2 v[2:3], v[0:1], off
	v_add_u32_e32 v0, s22, v4
	ds_read_b128 v[0:3], v0
	s_waitcnt lgkmcnt(0)
	v_mov_b32_e32 v6, v1
	v_mov_b32_e32 v7, v2
	v_mov_b32_e32 v8, v0
	v_mov_b32_e32 v9, v3
	v_pk_add_f32 v[6:7], v[6:7], v[8:9]
	s_nop 0
	v_add_f32_e32 v5, v6, v7
	s_nop 1
	v_add_f32_dpp v5, v5, v5 quad_perm:[1,0,3,2] row_mask:0xf bank_mask:0xf
	s_nop 1
	v_add_f32_dpp v5, v5, v5 quad_perm:[2,3,0,1] row_mask:0xf bank_mask:0xf
	s_nop 1
	v_add_f32_dpp v5, v5, v5 row_half_mirror row_mask:0xf bank_mask:0xf
	s_nop 1
	v_add_f32_dpp v5, v5, v5 row_mirror row_mask:0xf bank_mask:0xf
	v_mov_b32_e32 v6, v5
	s_nop 1
	v_permlane16_swap_b32_e32 v5, v6
	v_add_f32_e32 v5, v5, v6
	v_mov_b32_e32 v6, v5
	s_nop 1
	v_permlane32_swap_b32_e32 v5, v6
	v_add_f32_e32 v5, v5, v6
	v_fmamk_f32 v1, v5, 0xbb800000, v1
	v_fmamk_f32 v0, v5, 0xbb800000, v0
	v_fmamk_f32 v3, v5, 0xbb800000, v3
	v_fmac_f32_e32 v2, 0xbb800000, v5
	v_pk_mul_f32 v[6:7], v[2:3], v[2:3]
	v_pk_mul_f32 v[8:9], v[0:1], v[0:1]
	s_nop 0
	v_pk_mov_b32 v[10:11], v[8:9], v[6:7] op_sel:[1,0]
	v_mov_b32_e32 v9, v7
	v_pk_add_f32 v[6:7], v[10:11], v[8:9]
	s_nop 0
	v_add_f32_e32 v5, v6, v7
	s_nop 1
	v_add_f32_dpp v5, v5, v5 quad_perm:[1,0,3,2] row_mask:0xf bank_mask:0xf
	s_nop 1
	v_add_f32_dpp v5, v5, v5 quad_perm:[2,3,0,1] row_mask:0xf bank_mask:0xf
	s_nop 1
	v_add_f32_dpp v5, v5, v5 row_half_mirror row_mask:0xf bank_mask:0xf
	s_nop 1
	v_add_f32_dpp v5, v5, v5 row_mirror row_mask:0xf bank_mask:0xf
	v_mov_b32_e32 v6, v5
	s_nop 1
	v_permlane16_swap_b32_e32 v5, v6
	v_add_f32_e32 v5, v5, v6
	v_mov_b32_e32 v6, v5
	s_nop 1
	v_permlane32_swap_b32_e32 v5, v6
	v_add_f32_e32 v5, v5, v6
	v_fmamk_f32 v5, v5, 0x3b800000, v251
	v_cmp_gt_f32_e32 vcc, s19, v5
	v_mul_f32_e32 v6, 0x4f800000, v5
	s_nop 0
	v_cndmask_b32_e32 v5, v5, v6, vcc
	v_sqrt_f32_e32 v6, v5
	s_nop 0
	v_add_u32_e32 v7, -1, v6
	v_fma_f32 v8, -v7, v6, v5
	v_cmp_ge_f32_e64 s[2:3], 0, v8
	v_add_u32_e32 v8, 1, v6
	s_nop 0
	v_cndmask_b32_e64 v7, v6, v7, s[2:3]
	v_fma_f32 v6, -v8, v6, v5
	v_cmp_lt_f32_e64 s[2:3], 0, v6
	s_nop 1
	v_cndmask_b32_e64 v6, v7, v8, s[2:3]
	v_mul_f32_e32 v7, 0x37800000, v6
	v_cndmask_b32_e32 v6, v6, v7, vcc
	v_cmp_class_f32_e32 vcc, v5, v252
	s_nop 1
	v_cndmask_b32_e32 v5, v6, v5, vcc
	v_div_scale_f32 v6, s[2:3], v5, v5, 1.0
	v_rcp_f32_e32 v7, v6
	s_or_b32 s2, s54, s23
	v_or_b32_e32 v212, s2, v161
	v_fma_f32 v8, -v6, v7, 1.0
	v_fmac_f32_e32 v7, v8, v7
	v_div_scale_f32 v8, vcc, 1.0, v5, 1.0
	v_mul_f32_e32 v9, v8, v7
	v_fma_f32 v10, -v6, v9, v8
	v_fmac_f32_e32 v9, v10, v7
	v_fma_f32 v6, -v6, v9, v8
	v_div_fmas_f32 v6, v6, v7, v9
	v_div_fixup_f32 v6, v6, v5, 1.0
	v_pk_mul_f32 v[0:1], v[0:1], v[6:7] op_sel_hi:[1,0]
	s_waitcnt vmcnt(15)
	v_lshlrev_b32_e32 v8, 16, v78
	v_and_b32_e32 v9, 0xffff0000, v78
	v_pk_mul_f32 v[2:3], v[2:3], v[6:7] op_sel_hi:[1,0]
	v_lshlrev_b32_e32 v6, 16, v79
	v_and_b32_e32 v7, 0xffff0000, v79
	v_pk_mul_f32 v[0:1], v[0:1], v[8:9]
	v_pk_mul_f32 v[2:3], v[2:3], v[6:7]
	v_cvt_pk_bf16_f32 v0, v0, v1
	v_cvt_pk_bf16_f32 v1, v2, v3
	v_lshl_add_u64 v[2:3], v[212:213], 1, s[6:7]
	global_store_dwordx2 v[2:3], v[0:1], off
	v_add_u32_e32 v0, s26, v4
	ds_read_b128 v[0:3], v0
	s_waitcnt lgkmcnt(0)
	v_mov_b32_e32 v6, v1
	v_mov_b32_e32 v7, v2
	v_mov_b32_e32 v8, v0
	v_mov_b32_e32 v9, v3
	v_pk_add_f32 v[6:7], v[6:7], v[8:9]
	s_nop 0
	v_add_f32_e32 v5, v6, v7
	s_nop 1
	v_add_f32_dpp v5, v5, v5 quad_perm:[1,0,3,2] row_mask:0xf bank_mask:0xf
	s_nop 1
	v_add_f32_dpp v5, v5, v5 quad_perm:[2,3,0,1] row_mask:0xf bank_mask:0xf
	s_nop 1
	v_add_f32_dpp v5, v5, v5 row_half_mirror row_mask:0xf bank_mask:0xf
	s_nop 1
	v_add_f32_dpp v5, v5, v5 row_mirror row_mask:0xf bank_mask:0xf
	v_mov_b32_e32 v6, v5
	s_nop 1
	v_permlane16_swap_b32_e32 v5, v6
	v_add_f32_e32 v5, v5, v6
	v_mov_b32_e32 v6, v5
	s_nop 1
	v_permlane32_swap_b32_e32 v5, v6
	v_add_f32_e32 v5, v5, v6
	v_fmamk_f32 v1, v5, 0xbb800000, v1
	v_fmamk_f32 v0, v5, 0xbb800000, v0
	v_fmamk_f32 v3, v5, 0xbb800000, v3
	v_fmac_f32_e32 v2, 0xbb800000, v5
	v_pk_mul_f32 v[6:7], v[2:3], v[2:3]
	v_pk_mul_f32 v[8:9], v[0:1], v[0:1]
	s_nop 0
	v_pk_mov_b32 v[10:11], v[8:9], v[6:7] op_sel:[1,0]
	v_mov_b32_e32 v9, v7
	v_pk_add_f32 v[6:7], v[10:11], v[8:9]
	s_nop 0
	v_add_f32_e32 v5, v6, v7
	s_nop 1
	v_add_f32_dpp v5, v5, v5 quad_perm:[1,0,3,2] row_mask:0xf bank_mask:0xf
	s_nop 1
	v_add_f32_dpp v5, v5, v5 quad_perm:[2,3,0,1] row_mask:0xf bank_mask:0xf
	s_nop 1
	v_add_f32_dpp v5, v5, v5 row_half_mirror row_mask:0xf bank_mask:0xf
	s_nop 1
	v_add_f32_dpp v5, v5, v5 row_mirror row_mask:0xf bank_mask:0xf
	v_mov_b32_e32 v6, v5
	s_nop 1
	v_permlane16_swap_b32_e32 v5, v6
	v_add_f32_e32 v5, v5, v6
	v_mov_b32_e32 v6, v5
	s_nop 1
	v_permlane32_swap_b32_e32 v5, v6
	v_add_f32_e32 v5, v5, v6
	v_fmamk_f32 v5, v5, 0x3b800000, v251
	v_cmp_gt_f32_e32 vcc, s19, v5
	v_mul_f32_e32 v6, 0x4f800000, v5
	s_nop 0
	v_cndmask_b32_e32 v5, v5, v6, vcc
	v_sqrt_f32_e32 v6, v5
	s_nop 0
	v_add_u32_e32 v7, -1, v6
	v_fma_f32 v8, -v7, v6, v5
	v_cmp_ge_f32_e64 s[2:3], 0, v8
	v_add_u32_e32 v8, 1, v6
	s_nop 0
	v_cndmask_b32_e64 v7, v6, v7, s[2:3]
	v_fma_f32 v6, -v8, v6, v5
	v_cmp_lt_f32_e64 s[2:3], 0, v6
	s_nop 1
	v_cndmask_b32_e64 v6, v7, v8, s[2:3]
	v_mul_f32_e32 v7, 0x37800000, v6
	v_cndmask_b32_e32 v6, v6, v7, vcc
	v_cmp_class_f32_e32 vcc, v5, v252
	s_nop 1
	v_cndmask_b32_e32 v5, v6, v5, vcc
	v_div_scale_f32 v6, s[2:3], v5, v5, 1.0
	v_rcp_f32_e32 v7, v6
	s_or_b32 s2, s54, s27
	v_or_b32_e32 v212, s2, v161
	v_fma_f32 v8, -v6, v7, 1.0
	v_fmac_f32_e32 v7, v8, v7
	v_div_scale_f32 v8, vcc, 1.0, v5, 1.0
	v_mul_f32_e32 v9, v8, v7
	v_fma_f32 v10, -v6, v9, v8
	v_fmac_f32_e32 v9, v10, v7
	v_fma_f32 v6, -v6, v9, v8
	v_div_fmas_f32 v6, v6, v7, v9
	v_div_fixup_f32 v6, v6, v5, 1.0
	v_pk_mul_f32 v[0:1], v[0:1], v[6:7] op_sel_hi:[1,0]
	s_waitcnt vmcnt(15)
	v_lshlrev_b32_e32 v8, 16, v76
	v_and_b32_e32 v9, 0xffff0000, v76
	v_pk_mul_f32 v[2:3], v[2:3], v[6:7] op_sel_hi:[1,0]
	v_lshlrev_b32_e32 v6, 16, v77
	v_and_b32_e32 v7, 0xffff0000, v77
	v_pk_mul_f32 v[0:1], v[0:1], v[8:9]
	v_pk_mul_f32 v[2:3], v[2:3], v[6:7]
	v_cvt_pk_bf16_f32 v0, v0, v1
	v_cvt_pk_bf16_f32 v1, v2, v3
	v_lshl_add_u64 v[2:3], v[212:213], 1, s[6:7]
	global_store_dwordx2 v[2:3], v[0:1], off
	v_add_u32_e32 v0, s30, v4
	ds_read_b128 v[0:3], v0
	s_waitcnt lgkmcnt(0)
	v_mov_b32_e32 v6, v1
	v_mov_b32_e32 v7, v2
	v_mov_b32_e32 v8, v0
	v_mov_b32_e32 v9, v3
	v_pk_add_f32 v[6:7], v[6:7], v[8:9]
	s_nop 0
	v_add_f32_e32 v5, v6, v7
	s_nop 1
	v_add_f32_dpp v5, v5, v5 quad_perm:[1,0,3,2] row_mask:0xf bank_mask:0xf
	s_nop 1
	v_add_f32_dpp v5, v5, v5 quad_perm:[2,3,0,1] row_mask:0xf bank_mask:0xf
	s_nop 1
	v_add_f32_dpp v5, v5, v5 row_half_mirror row_mask:0xf bank_mask:0xf
	s_nop 1
	v_add_f32_dpp v5, v5, v5 row_mirror row_mask:0xf bank_mask:0xf
	v_mov_b32_e32 v6, v5
	s_nop 1
	v_permlane16_swap_b32_e32 v5, v6
	v_add_f32_e32 v5, v5, v6
	v_mov_b32_e32 v6, v5
	s_nop 1
	v_permlane32_swap_b32_e32 v5, v6
	v_add_f32_e32 v5, v5, v6
	v_fmamk_f32 v1, v5, 0xbb800000, v1
	v_fmamk_f32 v0, v5, 0xbb800000, v0
	v_fmamk_f32 v3, v5, 0xbb800000, v3
	v_fmac_f32_e32 v2, 0xbb800000, v5
	v_pk_mul_f32 v[6:7], v[2:3], v[2:3]
	v_pk_mul_f32 v[8:9], v[0:1], v[0:1]
	s_nop 0
	v_pk_mov_b32 v[10:11], v[8:9], v[6:7] op_sel:[1,0]
	v_mov_b32_e32 v9, v7
	v_pk_add_f32 v[6:7], v[10:11], v[8:9]
	s_nop 0
	v_add_f32_e32 v5, v6, v7
	s_nop 1
	v_add_f32_dpp v5, v5, v5 quad_perm:[1,0,3,2] row_mask:0xf bank_mask:0xf
	s_nop 1
	v_add_f32_dpp v5, v5, v5 quad_perm:[2,3,0,1] row_mask:0xf bank_mask:0xf
	s_nop 1
	v_add_f32_dpp v5, v5, v5 row_half_mirror row_mask:0xf bank_mask:0xf
	s_nop 1
	v_add_f32_dpp v5, v5, v5 row_mirror row_mask:0xf bank_mask:0xf
	v_mov_b32_e32 v6, v5
	s_nop 1
	v_permlane16_swap_b32_e32 v5, v6
	v_add_f32_e32 v5, v5, v6
	v_mov_b32_e32 v6, v5
	s_nop 1
	v_permlane32_swap_b32_e32 v5, v6
	v_add_f32_e32 v5, v5, v6
	v_fmamk_f32 v5, v5, 0x3b800000, v251
	v_cmp_gt_f32_e32 vcc, s19, v5
	v_mul_f32_e32 v6, 0x4f800000, v5
	s_nop 0
	v_cndmask_b32_e32 v5, v5, v6, vcc
	v_sqrt_f32_e32 v6, v5
	s_nop 0
	v_add_u32_e32 v7, -1, v6
	v_fma_f32 v8, -v7, v6, v5
	v_cmp_ge_f32_e64 s[2:3], 0, v8
	v_add_u32_e32 v8, 1, v6
	s_nop 0
	v_cndmask_b32_e64 v7, v6, v7, s[2:3]
	v_fma_f32 v6, -v8, v6, v5
	v_cmp_lt_f32_e64 s[2:3], 0, v6
	s_nop 1
	v_cndmask_b32_e64 v6, v7, v8, s[2:3]
	v_mul_f32_e32 v7, 0x37800000, v6
	v_cndmask_b32_e32 v6, v6, v7, vcc
	v_cmp_class_f32_e32 vcc, v5, v252
	s_nop 1
	v_cndmask_b32_e32 v5, v6, v5, vcc
	v_div_scale_f32 v6, s[2:3], v5, v5, 1.0
	v_rcp_f32_e32 v7, v6
	s_or_b32 s2, s54, s31
	v_or_b32_e32 v212, s2, v161
	v_fma_f32 v8, -v6, v7, 1.0
	v_fmac_f32_e32 v7, v8, v7
	v_div_scale_f32 v8, vcc, 1.0, v5, 1.0
	v_mul_f32_e32 v9, v8, v7
	v_fma_f32 v10, -v6, v9, v8
	v_fmac_f32_e32 v9, v10, v7
	v_fma_f32 v6, -v6, v9, v8
	v_div_fmas_f32 v6, v6, v7, v9
	v_div_fixup_f32 v6, v6, v5, 1.0
	v_pk_mul_f32 v[0:1], v[0:1], v[6:7] op_sel_hi:[1,0]
	s_waitcnt vmcnt(15)
	v_lshlrev_b32_e32 v8, 16, v74
	v_and_b32_e32 v9, 0xffff0000, v74
	v_pk_mul_f32 v[2:3], v[2:3], v[6:7] op_sel_hi:[1,0]
	v_lshlrev_b32_e32 v6, 16, v75
	v_and_b32_e32 v7, 0xffff0000, v75
	v_pk_mul_f32 v[0:1], v[0:1], v[8:9]
	v_pk_mul_f32 v[2:3], v[2:3], v[6:7]
	v_cvt_pk_bf16_f32 v0, v0, v1
	v_cvt_pk_bf16_f32 v1, v2, v3
	v_lshl_add_u64 v[2:3], v[212:213], 1, s[6:7]
	global_store_dwordx2 v[2:3], v[0:1], off
	v_add_u32_e32 v0, s37, v4
	ds_read_b128 v[0:3], v0
	s_waitcnt lgkmcnt(0)
	v_mov_b32_e32 v6, v1
	v_mov_b32_e32 v7, v2
	v_mov_b32_e32 v8, v0
	v_mov_b32_e32 v9, v3
	v_pk_add_f32 v[6:7], v[6:7], v[8:9]
	s_nop 0
	v_add_f32_e32 v5, v6, v7
	s_nop 1
	v_add_f32_dpp v5, v5, v5 quad_perm:[1,0,3,2] row_mask:0xf bank_mask:0xf
	s_nop 1
	v_add_f32_dpp v5, v5, v5 quad_perm:[2,3,0,1] row_mask:0xf bank_mask:0xf
	s_nop 1
	v_add_f32_dpp v5, v5, v5 row_half_mirror row_mask:0xf bank_mask:0xf
	s_nop 1
	v_add_f32_dpp v5, v5, v5 row_mirror row_mask:0xf bank_mask:0xf
	v_mov_b32_e32 v6, v5
	s_nop 1
	v_permlane16_swap_b32_e32 v5, v6
	v_add_f32_e32 v5, v5, v6
	v_mov_b32_e32 v6, v5
	s_nop 1
	v_permlane32_swap_b32_e32 v5, v6
	v_add_f32_e32 v5, v5, v6
	v_fmamk_f32 v1, v5, 0xbb800000, v1
	v_fmamk_f32 v0, v5, 0xbb800000, v0
	v_fmamk_f32 v3, v5, 0xbb800000, v3
	v_fmac_f32_e32 v2, 0xbb800000, v5
	v_pk_mul_f32 v[6:7], v[2:3], v[2:3]
	v_pk_mul_f32 v[8:9], v[0:1], v[0:1]
	s_nop 0
	v_pk_mov_b32 v[10:11], v[8:9], v[6:7] op_sel:[1,0]
	v_mov_b32_e32 v9, v7
	v_pk_add_f32 v[6:7], v[10:11], v[8:9]
	s_nop 0
	v_add_f32_e32 v5, v6, v7
	s_nop 1
	v_add_f32_dpp v5, v5, v5 quad_perm:[1,0,3,2] row_mask:0xf bank_mask:0xf
	s_nop 1
	v_add_f32_dpp v5, v5, v5 quad_perm:[2,3,0,1] row_mask:0xf bank_mask:0xf
	s_nop 1
	v_add_f32_dpp v5, v5, v5 row_half_mirror row_mask:0xf bank_mask:0xf
	s_nop 1
	v_add_f32_dpp v5, v5, v5 row_mirror row_mask:0xf bank_mask:0xf
	v_mov_b32_e32 v6, v5
	s_nop 1
	v_permlane16_swap_b32_e32 v5, v6
	v_add_f32_e32 v5, v5, v6
	v_mov_b32_e32 v6, v5
	s_nop 1
	v_permlane32_swap_b32_e32 v5, v6
	v_add_f32_e32 v5, v5, v6
	v_fmamk_f32 v5, v5, 0x3b800000, v251
	v_cmp_gt_f32_e32 vcc, s19, v5
	v_mul_f32_e32 v6, 0x4f800000, v5
	s_nop 0
	v_cndmask_b32_e32 v5, v5, v6, vcc
	v_sqrt_f32_e32 v6, v5
	s_nop 0
	v_add_u32_e32 v7, -1, v6
	v_fma_f32 v8, -v7, v6, v5
	v_cmp_ge_f32_e64 s[2:3], 0, v8
	v_add_u32_e32 v8, 1, v6
	s_nop 0
	v_cndmask_b32_e64 v7, v6, v7, s[2:3]
	v_fma_f32 v6, -v8, v6, v5
	v_cmp_lt_f32_e64 s[2:3], 0, v6
	s_nop 1
	v_cndmask_b32_e64 v6, v7, v8, s[2:3]
	v_mul_f32_e32 v7, 0x37800000, v6
	v_cndmask_b32_e32 v6, v6, v7, vcc
	v_cmp_class_f32_e32 vcc, v5, v252
	s_nop 1
	v_cndmask_b32_e32 v5, v6, v5, vcc
	v_div_scale_f32 v6, s[2:3], v5, v5, 1.0
	v_rcp_f32_e32 v7, v6
	s_or_b32 s2, s54, s38
	v_or_b32_e32 v212, s2, v161
	v_fma_f32 v8, -v6, v7, 1.0
	v_fmac_f32_e32 v7, v8, v7
	v_div_scale_f32 v8, vcc, 1.0, v5, 1.0
	v_mul_f32_e32 v9, v8, v7
	v_fma_f32 v10, -v6, v9, v8
	v_fmac_f32_e32 v9, v10, v7
	v_fma_f32 v6, -v6, v9, v8
	v_div_fmas_f32 v6, v6, v7, v9
	v_div_fixup_f32 v6, v6, v5, 1.0
	v_pk_mul_f32 v[0:1], v[0:1], v[6:7] op_sel_hi:[1,0]
	s_waitcnt vmcnt(15)
	v_lshlrev_b32_e32 v8, 16, v72
	v_and_b32_e32 v9, 0xffff0000, v72
	v_pk_mul_f32 v[2:3], v[2:3], v[6:7] op_sel_hi:[1,0]
	v_lshlrev_b32_e32 v6, 16, v73
	v_and_b32_e32 v7, 0xffff0000, v73
	v_pk_mul_f32 v[0:1], v[0:1], v[8:9]
	v_pk_mul_f32 v[2:3], v[2:3], v[6:7]
	v_cvt_pk_bf16_f32 v0, v0, v1
	v_cvt_pk_bf16_f32 v1, v2, v3
	v_lshl_add_u64 v[2:3], v[212:213], 1, s[6:7]
	global_store_dwordx2 v[2:3], v[0:1], off
	v_add_u32_e32 v0, s40, v4
	ds_read_b128 v[0:3], v0
	s_waitcnt lgkmcnt(0)
	v_mov_b32_e32 v6, v1
	v_mov_b32_e32 v7, v2
	v_mov_b32_e32 v8, v0
	v_mov_b32_e32 v9, v3
	v_pk_add_f32 v[6:7], v[6:7], v[8:9]
	s_nop 0
	v_add_f32_e32 v5, v6, v7
	s_nop 1
	v_add_f32_dpp v5, v5, v5 quad_perm:[1,0,3,2] row_mask:0xf bank_mask:0xf
	s_nop 1
	v_add_f32_dpp v5, v5, v5 quad_perm:[2,3,0,1] row_mask:0xf bank_mask:0xf
	s_nop 1
	v_add_f32_dpp v5, v5, v5 row_half_mirror row_mask:0xf bank_mask:0xf
	s_nop 1
	v_add_f32_dpp v5, v5, v5 row_mirror row_mask:0xf bank_mask:0xf
	v_mov_b32_e32 v6, v5
	s_nop 1
	v_permlane16_swap_b32_e32 v5, v6
	v_add_f32_e32 v5, v5, v6
	v_mov_b32_e32 v6, v5
	s_nop 1
	v_permlane32_swap_b32_e32 v5, v6
	v_add_f32_e32 v5, v5, v6
	v_fmamk_f32 v1, v5, 0xbb800000, v1
	v_fmamk_f32 v0, v5, 0xbb800000, v0
	v_fmamk_f32 v3, v5, 0xbb800000, v3
	v_fmac_f32_e32 v2, 0xbb800000, v5
	v_pk_mul_f32 v[6:7], v[2:3], v[2:3]
	v_pk_mul_f32 v[8:9], v[0:1], v[0:1]
	s_nop 0
	v_pk_mov_b32 v[10:11], v[8:9], v[6:7] op_sel:[1,0]
	v_mov_b32_e32 v9, v7
	v_pk_add_f32 v[6:7], v[10:11], v[8:9]
	s_nop 0
	v_add_f32_e32 v5, v6, v7
	s_nop 1
	v_add_f32_dpp v5, v5, v5 quad_perm:[1,0,3,2] row_mask:0xf bank_mask:0xf
	s_nop 1
	v_add_f32_dpp v5, v5, v5 quad_perm:[2,3,0,1] row_mask:0xf bank_mask:0xf
	s_nop 1
	v_add_f32_dpp v5, v5, v5 row_half_mirror row_mask:0xf bank_mask:0xf
	s_nop 1
	v_add_f32_dpp v5, v5, v5 row_mirror row_mask:0xf bank_mask:0xf
	v_mov_b32_e32 v6, v5
	s_nop 1
	v_permlane16_swap_b32_e32 v5, v6
	v_add_f32_e32 v5, v5, v6
	v_mov_b32_e32 v6, v5
	s_nop 1
	v_permlane32_swap_b32_e32 v5, v6
	v_add_f32_e32 v5, v5, v6
	v_fmamk_f32 v5, v5, 0x3b800000, v251
	v_cmp_gt_f32_e32 vcc, s19, v5
	v_mul_f32_e32 v6, 0x4f800000, v5
	s_nop 0
	v_cndmask_b32_e32 v5, v5, v6, vcc
	v_sqrt_f32_e32 v6, v5
	s_nop 0
	v_add_u32_e32 v7, -1, v6
	v_fma_f32 v8, -v7, v6, v5
	v_cmp_ge_f32_e64 s[2:3], 0, v8
	v_add_u32_e32 v8, 1, v6
	s_nop 0
	v_cndmask_b32_e64 v7, v6, v7, s[2:3]
	v_fma_f32 v6, -v8, v6, v5
	v_cmp_lt_f32_e64 s[2:3], 0, v6
	s_nop 1
	v_cndmask_b32_e64 v6, v7, v8, s[2:3]
	v_mul_f32_e32 v7, 0x37800000, v6
	v_cndmask_b32_e32 v6, v6, v7, vcc
	v_cmp_class_f32_e32 vcc, v5, v252
	s_nop 1
	v_cndmask_b32_e32 v5, v6, v5, vcc
	v_div_scale_f32 v6, s[2:3], v5, v5, 1.0
	v_rcp_f32_e32 v7, v6
	s_or_b32 s2, s54, s41
	v_or_b32_e32 v212, s2, v161
	v_fma_f32 v8, -v6, v7, 1.0
	v_fmac_f32_e32 v7, v8, v7
	v_div_scale_f32 v8, vcc, 1.0, v5, 1.0
	v_mul_f32_e32 v9, v8, v7
	v_fma_f32 v10, -v6, v9, v8
	v_fmac_f32_e32 v9, v10, v7
	v_fma_f32 v6, -v6, v9, v8
	v_div_fmas_f32 v6, v6, v7, v9
	v_div_fixup_f32 v6, v6, v5, 1.0
	v_pk_mul_f32 v[0:1], v[0:1], v[6:7] op_sel_hi:[1,0]
	s_waitcnt vmcnt(15)
	v_lshlrev_b32_e32 v8, 16, v70
	v_and_b32_e32 v9, 0xffff0000, v70
	v_pk_mul_f32 v[2:3], v[2:3], v[6:7] op_sel_hi:[1,0]
	v_lshlrev_b32_e32 v6, 16, v71
	v_and_b32_e32 v7, 0xffff0000, v71
	v_pk_mul_f32 v[0:1], v[0:1], v[8:9]
	v_pk_mul_f32 v[2:3], v[2:3], v[6:7]
	v_cvt_pk_bf16_f32 v0, v0, v1
	v_cvt_pk_bf16_f32 v1, v2, v3
	v_lshl_add_u64 v[2:3], v[212:213], 1, s[6:7]
	global_store_dwordx2 v[2:3], v[0:1], off
	v_add_u32_e32 v0, s48, v4
	ds_read_b128 v[0:3], v0
	s_waitcnt lgkmcnt(0)
	v_mov_b32_e32 v6, v1
	v_mov_b32_e32 v7, v2
	v_mov_b32_e32 v8, v0
	v_mov_b32_e32 v9, v3
	v_pk_add_f32 v[6:7], v[6:7], v[8:9]
	s_nop 0
	v_add_f32_e32 v5, v6, v7
	s_nop 1
	v_add_f32_dpp v5, v5, v5 quad_perm:[1,0,3,2] row_mask:0xf bank_mask:0xf
	s_nop 1
	v_add_f32_dpp v5, v5, v5 quad_perm:[2,3,0,1] row_mask:0xf bank_mask:0xf
	s_nop 1
	v_add_f32_dpp v5, v5, v5 row_half_mirror row_mask:0xf bank_mask:0xf
	s_nop 1
	v_add_f32_dpp v5, v5, v5 row_mirror row_mask:0xf bank_mask:0xf
	v_mov_b32_e32 v6, v5
	s_nop 1
	v_permlane16_swap_b32_e32 v5, v6
	v_add_f32_e32 v5, v5, v6
	v_mov_b32_e32 v6, v5
	s_nop 1
	v_permlane32_swap_b32_e32 v5, v6
	v_add_f32_e32 v5, v5, v6
	v_fmamk_f32 v1, v5, 0xbb800000, v1
	v_fmamk_f32 v0, v5, 0xbb800000, v0
	v_fmamk_f32 v3, v5, 0xbb800000, v3
	v_fmac_f32_e32 v2, 0xbb800000, v5
	v_pk_mul_f32 v[6:7], v[2:3], v[2:3]
	v_pk_mul_f32 v[8:9], v[0:1], v[0:1]
	s_nop 0
	v_pk_mov_b32 v[10:11], v[8:9], v[6:7] op_sel:[1,0]
	v_mov_b32_e32 v9, v7
	v_pk_add_f32 v[6:7], v[10:11], v[8:9]
	s_nop 0
	v_add_f32_e32 v5, v6, v7
	s_nop 1
	v_add_f32_dpp v5, v5, v5 quad_perm:[1,0,3,2] row_mask:0xf bank_mask:0xf
	s_nop 1
	v_add_f32_dpp v5, v5, v5 quad_perm:[2,3,0,1] row_mask:0xf bank_mask:0xf
	s_nop 1
	v_add_f32_dpp v5, v5, v5 row_half_mirror row_mask:0xf bank_mask:0xf
	s_nop 1
	v_add_f32_dpp v5, v5, v5 row_mirror row_mask:0xf bank_mask:0xf
	v_mov_b32_e32 v6, v5
	s_nop 1
	v_permlane16_swap_b32_e32 v5, v6
	v_add_f32_e32 v5, v5, v6
	v_mov_b32_e32 v6, v5
	s_nop 1
	v_permlane32_swap_b32_e32 v5, v6
	v_add_f32_e32 v5, v5, v6
	v_fmamk_f32 v5, v5, 0x3b800000, v251
	v_cmp_gt_f32_e32 vcc, s19, v5
	v_mul_f32_e32 v6, 0x4f800000, v5
	s_nop 0
	v_cndmask_b32_e32 v5, v5, v6, vcc
	v_sqrt_f32_e32 v6, v5
	s_nop 0
	v_add_u32_e32 v7, -1, v6
	v_fma_f32 v8, -v7, v6, v5
	v_cmp_ge_f32_e64 s[2:3], 0, v8
	v_add_u32_e32 v8, 1, v6
	s_nop 0
	v_cndmask_b32_e64 v7, v6, v7, s[2:3]
	v_fma_f32 v6, -v8, v6, v5
	v_cmp_lt_f32_e64 s[2:3], 0, v6
	s_nop 1
	v_cndmask_b32_e64 v6, v7, v8, s[2:3]
	v_mul_f32_e32 v7, 0x37800000, v6
	v_cndmask_b32_e32 v6, v6, v7, vcc
	v_cmp_class_f32_e32 vcc, v5, v252
	s_nop 1
	v_cndmask_b32_e32 v5, v6, v5, vcc
	v_div_scale_f32 v6, s[2:3], v5, v5, 1.0
	v_rcp_f32_e32 v7, v6
	s_or_b32 s2, s54, s49
	v_or_b32_e32 v212, s2, v161
	v_fma_f32 v8, -v6, v7, 1.0
	v_fmac_f32_e32 v7, v8, v7
	v_div_scale_f32 v8, vcc, 1.0, v5, 1.0
	v_mul_f32_e32 v9, v8, v7
	v_fma_f32 v10, -v6, v9, v8
	v_fmac_f32_e32 v9, v10, v7
	v_fma_f32 v6, -v6, v9, v8
	v_div_fmas_f32 v6, v6, v7, v9
	v_div_fixup_f32 v6, v6, v5, 1.0
	v_pk_mul_f32 v[0:1], v[0:1], v[6:7] op_sel_hi:[1,0]
	s_waitcnt vmcnt(15)
	v_lshlrev_b32_e32 v8, 16, v68
	v_and_b32_e32 v9, 0xffff0000, v68
	v_pk_mul_f32 v[2:3], v[2:3], v[6:7] op_sel_hi:[1,0]
	v_lshlrev_b32_e32 v6, 16, v69
	v_and_b32_e32 v7, 0xffff0000, v69
	v_pk_mul_f32 v[0:1], v[0:1], v[8:9]
	v_pk_mul_f32 v[2:3], v[2:3], v[6:7]
	v_cvt_pk_bf16_f32 v0, v0, v1
	v_cvt_pk_bf16_f32 v1, v2, v3
	v_lshl_add_u64 v[2:3], v[212:213], 1, s[6:7]
	global_store_dwordx2 v[2:3], v[0:1], off
	v_add_u32_e32 v0, s50, v4
	ds_read_b128 v[0:3], v0
	s_waitcnt lgkmcnt(0)
	v_mov_b32_e32 v6, v1
	v_mov_b32_e32 v7, v2
	v_mov_b32_e32 v8, v0
	v_mov_b32_e32 v9, v3
	v_pk_add_f32 v[6:7], v[6:7], v[8:9]
	s_nop 0
	v_add_f32_e32 v5, v6, v7
	s_nop 1
	v_add_f32_dpp v5, v5, v5 quad_perm:[1,0,3,2] row_mask:0xf bank_mask:0xf
	s_nop 1
	v_add_f32_dpp v5, v5, v5 quad_perm:[2,3,0,1] row_mask:0xf bank_mask:0xf
	s_nop 1
	v_add_f32_dpp v5, v5, v5 row_half_mirror row_mask:0xf bank_mask:0xf
	s_nop 1
	v_add_f32_dpp v5, v5, v5 row_mirror row_mask:0xf bank_mask:0xf
	v_mov_b32_e32 v6, v5
	s_nop 1
	v_permlane16_swap_b32_e32 v5, v6
	v_add_f32_e32 v5, v5, v6
	v_mov_b32_e32 v6, v5
	s_nop 1
	v_permlane32_swap_b32_e32 v5, v6
	v_add_f32_e32 v5, v5, v6
	v_fmamk_f32 v1, v5, 0xbb800000, v1
	v_fmamk_f32 v0, v5, 0xbb800000, v0
	v_fmamk_f32 v3, v5, 0xbb800000, v3
	v_fmac_f32_e32 v2, 0xbb800000, v5
	v_pk_mul_f32 v[6:7], v[2:3], v[2:3]
	v_pk_mul_f32 v[8:9], v[0:1], v[0:1]
	s_nop 0
	v_pk_mov_b32 v[10:11], v[8:9], v[6:7] op_sel:[1,0]
	v_mov_b32_e32 v9, v7
	v_pk_add_f32 v[6:7], v[10:11], v[8:9]
	s_nop 0
	v_add_f32_e32 v5, v6, v7
	s_nop 1
	v_add_f32_dpp v5, v5, v5 quad_perm:[1,0,3,2] row_mask:0xf bank_mask:0xf
	s_nop 1
	v_add_f32_dpp v5, v5, v5 quad_perm:[2,3,0,1] row_mask:0xf bank_mask:0xf
	s_nop 1
	v_add_f32_dpp v5, v5, v5 row_half_mirror row_mask:0xf bank_mask:0xf
	s_nop 1
	v_add_f32_dpp v5, v5, v5 row_mirror row_mask:0xf bank_mask:0xf
	v_mov_b32_e32 v6, v5
	s_nop 1
	v_permlane16_swap_b32_e32 v5, v6
	v_add_f32_e32 v5, v5, v6
	v_mov_b32_e32 v6, v5
	s_nop 1
	v_permlane32_swap_b32_e32 v5, v6
	v_add_f32_e32 v5, v5, v6
	v_fmamk_f32 v5, v5, 0x3b800000, v251
	v_cmp_gt_f32_e32 vcc, s19, v5
	v_mul_f32_e32 v6, 0x4f800000, v5
	s_nop 0
	v_cndmask_b32_e32 v5, v5, v6, vcc
	v_sqrt_f32_e32 v6, v5
	s_nop 0
	v_add_u32_e32 v7, -1, v6
	v_fma_f32 v8, -v7, v6, v5
	v_cmp_ge_f32_e64 s[2:3], 0, v8
	v_add_u32_e32 v8, 1, v6
	s_nop 0
	v_cndmask_b32_e64 v7, v6, v7, s[2:3]
	v_fma_f32 v6, -v8, v6, v5
	v_cmp_lt_f32_e64 s[2:3], 0, v6
	s_nop 1
	v_cndmask_b32_e64 v6, v7, v8, s[2:3]
	v_mul_f32_e32 v7, 0x37800000, v6
	v_cndmask_b32_e32 v6, v6, v7, vcc
	v_cmp_class_f32_e32 vcc, v5, v252
	s_nop 1
	v_cndmask_b32_e32 v5, v6, v5, vcc
	v_div_scale_f32 v6, s[2:3], v5, v5, 1.0
	v_rcp_f32_e32 v7, v6
	s_or_b32 s2, s54, s51
	v_or_b32_e32 v212, s2, v161
	v_fma_f32 v8, -v6, v7, 1.0
	v_fmac_f32_e32 v7, v8, v7
	v_div_scale_f32 v8, vcc, 1.0, v5, 1.0
	v_mul_f32_e32 v9, v8, v7
	v_fma_f32 v10, -v6, v9, v8
	v_fmac_f32_e32 v9, v10, v7
	v_fma_f32 v6, -v6, v9, v8
	v_div_fmas_f32 v6, v6, v7, v9
	v_div_fixup_f32 v6, v6, v5, 1.0
	v_pk_mul_f32 v[0:1], v[0:1], v[6:7] op_sel_hi:[1,0]
	s_waitcnt vmcnt(15)
	v_lshlrev_b32_e32 v8, 16, v66
	v_and_b32_e32 v9, 0xffff0000, v66
	v_pk_mul_f32 v[2:3], v[2:3], v[6:7] op_sel_hi:[1,0]
	v_lshlrev_b32_e32 v6, 16, v67
	v_and_b32_e32 v7, 0xffff0000, v67
	v_pk_mul_f32 v[0:1], v[0:1], v[8:9]
	v_pk_mul_f32 v[2:3], v[2:3], v[6:7]
	v_cvt_pk_bf16_f32 v0, v0, v1
	v_cvt_pk_bf16_f32 v1, v2, v3
	v_lshl_add_u64 v[2:3], v[212:213], 1, s[6:7]
	global_store_dwordx2 v[2:3], v[0:1], off
	v_add_u32_e32 v0, s52, v4
	ds_read_b128 v[0:3], v0
	s_waitcnt lgkmcnt(0)
	v_mov_b32_e32 v4, v1
	v_mov_b32_e32 v5, v2
	v_mov_b32_e32 v6, v0
	v_mov_b32_e32 v7, v3
	v_pk_add_f32 v[4:5], v[4:5], v[6:7]
	s_nop 0
	v_add_f32_e32 v4, v4, v5
	s_nop 1
	v_add_f32_dpp v4, v4, v4 quad_perm:[1,0,3,2] row_mask:0xf bank_mask:0xf
	s_nop 1
	v_add_f32_dpp v4, v4, v4 quad_perm:[2,3,0,1] row_mask:0xf bank_mask:0xf
	s_nop 1
	v_add_f32_dpp v4, v4, v4 row_half_mirror row_mask:0xf bank_mask:0xf
	s_nop 1
	v_add_f32_dpp v4, v4, v4 row_mirror row_mask:0xf bank_mask:0xf
	v_mov_b32_e32 v5, v4
	s_nop 1
	v_permlane16_swap_b32_e32 v4, v5
	v_add_f32_e32 v4, v4, v5
	v_mov_b32_e32 v5, v4
	s_nop 1
	v_permlane32_swap_b32_e32 v4, v5
	v_add_f32_e32 v4, v4, v5
	v_fmamk_f32 v1, v4, 0xbb800000, v1
	v_fmamk_f32 v0, v4, 0xbb800000, v0
	v_fmamk_f32 v3, v4, 0xbb800000, v3
	v_fmac_f32_e32 v2, 0xbb800000, v4
	v_pk_mul_f32 v[4:5], v[2:3], v[2:3]
	v_pk_mul_f32 v[6:7], v[0:1], v[0:1]
	s_nop 0
	v_pk_mov_b32 v[8:9], v[6:7], v[4:5] op_sel:[1,0]
	v_mov_b32_e32 v7, v5
	v_pk_add_f32 v[4:5], v[8:9], v[6:7]
	s_nop 0
	v_add_f32_e32 v4, v4, v5
	s_nop 1
	v_add_f32_dpp v4, v4, v4 quad_perm:[1,0,3,2] row_mask:0xf bank_mask:0xf
	s_nop 1
	v_add_f32_dpp v4, v4, v4 quad_perm:[2,3,0,1] row_mask:0xf bank_mask:0xf
	s_nop 1
	v_add_f32_dpp v4, v4, v4 row_half_mirror row_mask:0xf bank_mask:0xf
	s_nop 1
	v_add_f32_dpp v4, v4, v4 row_mirror row_mask:0xf bank_mask:0xf
	v_mov_b32_e32 v5, v4
	s_nop 1
	v_permlane16_swap_b32_e32 v4, v5
	v_add_f32_e32 v4, v4, v5
	v_mov_b32_e32 v5, v4
	s_nop 1
	v_permlane32_swap_b32_e32 v4, v5
	v_add_f32_e32 v4, v4, v5
	v_fmamk_f32 v4, v4, 0x3b800000, v251
	v_cmp_gt_f32_e32 vcc, s19, v4
	v_mul_f32_e32 v5, 0x4f800000, v4
	s_nop 0
	v_cndmask_b32_e32 v4, v4, v5, vcc
	v_sqrt_f32_e32 v5, v4
	s_nop 0
	v_add_u32_e32 v6, -1, v5
	v_fma_f32 v7, -v6, v5, v4
	v_cmp_ge_f32_e64 s[2:3], 0, v7
	v_add_u32_e32 v7, 1, v5
	s_nop 0
	v_cndmask_b32_e64 v6, v5, v6, s[2:3]
	v_fma_f32 v5, -v7, v5, v4
	v_cmp_lt_f32_e64 s[2:3], 0, v5
	s_nop 1
	v_cndmask_b32_e64 v5, v6, v7, s[2:3]
	v_mul_f32_e32 v6, 0x37800000, v5
	v_cndmask_b32_e32 v5, v5, v6, vcc
	v_cmp_class_f32_e32 vcc, v4, v252
	s_nop 1
	v_cndmask_b32_e32 v4, v5, v4, vcc
	v_div_scale_f32 v5, s[2:3], v4, v4, 1.0
	v_rcp_f32_e32 v6, v5
	s_or_b32 s2, s54, s53
	v_or_b32_e32 v212, s2, v161
	v_fma_f32 v7, -v5, v6, 1.0
	v_fmac_f32_e32 v6, v7, v6
	v_div_scale_f32 v7, vcc, 1.0, v4, 1.0
	v_mul_f32_e32 v8, v7, v6
	v_fma_f32 v9, -v5, v8, v7
	v_fmac_f32_e32 v8, v9, v6
	v_fma_f32 v5, -v5, v8, v7
	v_div_fmas_f32 v5, v5, v6, v8
	v_div_fixup_f32 v4, v5, v4, 1.0
	v_pk_mul_f32 v[0:1], v[0:1], v[4:5] op_sel_hi:[1,0]
	s_waitcnt vmcnt(15)
	v_lshlrev_b32_e32 v6, 16, v64
	v_and_b32_e32 v7, 0xffff0000, v64
	v_pk_mul_f32 v[2:3], v[2:3], v[4:5] op_sel_hi:[1,0]
	v_lshlrev_b32_e32 v4, 16, v65
	v_and_b32_e32 v5, 0xffff0000, v65
	v_pk_mul_f32 v[0:1], v[0:1], v[6:7]
	v_pk_mul_f32 v[2:3], v[2:3], v[4:5]
	v_cvt_pk_bf16_f32 v0, v0, v1
	v_cvt_pk_bf16_f32 v1, v2, v3
	v_lshl_add_u64 v[2:3], v[212:213], 1, s[6:7]
	global_store_dwordx2 v[2:3], v[0:1], off
	s_andn2_b64 vcc, exec, s[4:5]
	s_cbranch_vccz .LBB0_663
